# H + attention loop instruction trims: ones operand kept in registers for the whole phase, V reads address v157 directly, uniform-branch mask fed from the compares, redundant canonicalising max dropped
# speedup vs baseline: 1.0052x; 1.0052x over previous
; #define LAS __attribute__((address_space(3)))
; __device__ __forceinline__ void attn_unit(const Params& p, LAS unsigned char* lds, int b, int h, int qb, int tid, int wid, int lane, u64& tacc, v4u& kA, v4u& vA, v4u& kB, v4u& vB, const bool first) {
;     const bf16* proj = (const bf16*)(p.ws + WS_PROJ); const u64* bm = (const u64*)((const unsigned char*)p.out + DO_BM); bf16* attn = (bf16*)(p.ws + WS_CA) + 512;
;     const int r32 = lane & 31, hi = lane >> 5;
;     const size_t rowbase = (size_t)b * SEQ; const int q0 = qb * 256;
;     LAS bf16* stg = (LAS bf16*)(lds + 32768) + wid * 2304;
;     const bf16* Qw = proj + (rowbase + q0 + wid * 32) * NPROJ + PC_Q + h * 64;
;     bf16x8 qr[4];
; #pragma unroll
;     for (int d0 = 0; d0 < 4; ++d0) qr[d0] = *(const bf16x8*)(Qw + (size_t)r32 * NPROJ + d0 * 16 + hi * 8);
;     const int NT = 4 * (qb + 1); const int tcw = 4 * qb + (wid >> 1);
;     const bf16* ksrc = (const bf16*)((const unsigned char*)p.out + DO_KBLK) + (size_t)(b * 8 + h) * 64 * 4096 + wid * 512 + lane * 8;
;     const bf16* vsrc = (const bf16*)((const unsigned char*)p.out + DO_VBLK) + (size_t)(b * 8 + h) * 64 * 4096 + wid * 512 + lane * 8;
;     const u64* bmq = bm + (rowbase + q0 + wid * 32 + r32) * 64;
;     const unsigned stoff = wid * 1024 + lane * 16;
;     const unsigned vboff = 8192 + ((lane >> 4) & 1) * 32 + (lane & 3) * 8 + (4 * hi + ((lane & 15) >> 2)) * 64;
;     float m = 0.f; bool started = false; f32x16 o0, o1, o2;
; #pragma unroll
;     for (int i = 0; i < 16; ++i) { o0[i] = 0.f; o1[i] = 0.f; o2[i] = 0.f; }
;     float negv = -1e30f; asm volatile("" : "+v"(negv));
;     const bf16x8 ones8 = (bf16x8){0x3f80, 0x3f80, 0x3f80, 0x3f80, 0x3f80, 0x3f80, 0x3f80, 0x3f80};
;     v4u mwc = *(const v4u*)bmq, mwn = mwc;
;     if (first) {
;         kB = *(const v4u*)ksrc; vB = *(const v4u*)vsrc;
;         kA = *(const v4u*)(ksrc + (size_t)4096); vA = *(const v4u*)(vsrc + (size_t)4096);
;         *(LAS v4u*)(lds + stoff) = kB; *(LAS v4u*)(lds + 8192 + stoff) = vB;
;         kB = *(const v4u*)(ksrc + (size_t)2 * 4096); vB = *(const v4u*)(vsrc + (size_t)2 * 4096);
;     }
.LBB0_3754:
	s_ashr_i32 s0, s85, 5
	s_ashr_i32 s1, s0, 31
	s_and_b32 s38, s85, 3
	s_bfe_u32 s2, s85, 0x30002
	s_lshl_b64 s[4:5], s[0:1], 12
	s_add_u32 s39, s4, s24
	s_addc_u32 s40, s5, 0
	s_lshl_b32 s0, s0, 3
	s_or_b32 s0, s0, s2
	s_ashr_i32 s1, s0, 31
	s_lshl_b64 s[0:1], s[0:1], 19
	s_lshl_b32 s9, s2, 6
	v_lshl_add_u64 v[180:181], v[162:163], 0, s[0:1]
	v_lshl_add_u64 v[182:183], v[164:165], 0, s[0:1]
	s_lshl_b32 s2, s2, 7
	s_or_b32 s41, s38, 8
	s_xor_b32 s42, s38, 15
	s_xor_b32 s43, s38, 7
	v_lshl_add_u64 v[184:185], v[180:181], 0, s[12:13]
	v_lshl_add_u64 v[186:187], v[182:183], 0, s[12:13]
	v_lshl_add_u64 v[188:189], v[180:181], 0, s[14:15]
	v_lshl_add_u64 v[190:191], v[182:183], 0, s[14:15]
	v_lshl_add_u64 v[192:193], v[166:167], 0, s[2:3]
	v_lshl_add_u64 v[194:195], v[168:169], 0, s[4:5]
	s_lshl_b32 s44, s9, 1
	s_mov_b32 s45, s3
	v_mov_b32_e32 v120, s8
	v_mov_b32_e32 v121, s8
	v_mov_b32_e32 v122, s8
	v_mov_b32_e32 v123, s8
	s_branch .LBB0_3756

.LBB0_3761:
	s_add_i32 s0, s51, 2
	s_sub_i32 s1, s0, s48
	s_min_u32 s2, s0, s1
	s_lshl_b64 s[0:1], s[2:3], 13
	v_lshl_add_u64 v[6:7], v[180:181], 0, s[0:1]
	v_lshl_add_u64 v[8:9], v[182:183], 0, s[0:1]
	s_mov_b32 m0, s70
	s_nop 0
	global_load_lds_dwordx4 v[6:7], off
	s_add_i32 m0, s70, 0x2000
	s_nop 0
	global_load_lds_dwordx4 v[8:9], off
	s_add_i32 s0, s51, 3
	s_sub_i32 s1, s0, s48
	s_min_u32 s2, s0, s1
	s_lshl_b64 s[0:1], s[2:3], 13
	v_lshl_add_u64 v[6:7], v[180:181], 0, s[0:1]
	v_lshl_add_u64 v[8:9], v[182:183], 0, s[0:1]
	s_add_i32 m0, s70, 0x4000
	s_nop 0
	global_load_lds_dwordx4 v[6:7], off
	s_add_i32 m0, s70, 0x6000
	s_nop 0
	global_load_lds_dwordx4 v[8:9], off
	s_cmp_gt_u32 s51, s47
	s_cbranch_scc1 .LBB0_3765
	ds_read_b128 v[6:9], v200
	ds_read_b128 v[10:13], v200 offset:512
	v_lshrrev_b32_e32 v1, v160, v152
	v_lshrrev_b32_e32 v14, v160, v153
	v_bitop3_b32 v228, v1, s27, v1 bitop3:0xc
	v_bitop3_b32 v229, v1, s28, v1 bitop3:0xc
	v_bitop3_b32 v230, v1, s29, v1 bitop3:0xc
	v_bitop3_b32 v231, v1, s30, v1 bitop3:0xc
	s_waitcnt lgkmcnt(1)
	v_mfma_f32_32x32x16_bf16 v[80:95], v[6:9], v[144:147], v[64:79]
	v_mul_u32_u24_e32 v228, 0xf000, v228
	v_mul_u32_u24_e32 v229, 0x7800, v229
	v_mul_u32_u24_e32 v230, 0x3c00, v230
	v_mul_u32_u24_e32 v231, 0x1e00, v231
	s_waitcnt lgkmcnt(0)
	v_mfma_f32_32x32x16_bf16 v[96:111], v[10:13], v[144:147], v[64:79]
	ds_read_b128 v[6:9], v200 offset:2048
	ds_read_b128 v[10:13], v200 offset:2560
	v_bitop3_b32 v232, v14, s27, v14 bitop3:0xc
	v_bitop3_b32 v233, v14, s28, v14 bitop3:0xc
	v_bitop3_b32 v234, v14, s29, v14 bitop3:0xc
	v_bitop3_b32 v235, v14, s30, v14 bitop3:0xc
	v_mul_u32_u24_e32 v232, 0xf000, v232
	v_mul_u32_u24_e32 v233, 0x7800, v233
	v_mul_u32_u24_e32 v234, 0x3c00, v234
	v_mul_u32_u24_e32 v235, 0x1e00, v235
	s_waitcnt lgkmcnt(1)
	v_mfma_f32_32x32x16_bf16 v[80:95], v[6:9], v[136:139], v[80:95]
	v_bitop3_b32 v236, v1, s31, v1 bitop3:0xc
	v_bitop3_b32 v237, v1, s33, v1 bitop3:0xc
	v_bitop3_b32 v238, v1, s34, v1 bitop3:0xc
	v_bitop3_b32 v239, v1, s35, v1 bitop3:0xc
	s_waitcnt lgkmcnt(0)
	v_mfma_f32_32x32x16_bf16 v[96:111], v[10:13], v[136:139], v[96:111]
	ds_read_b128 v[6:9], v200 offset:4096
	ds_read_b128 v[10:13], v200 offset:4608
	v_mul_u32_u24_e32 v236, 0xf00, v236
	v_mul_u32_u24_e32 v237, 0x780, v237
	v_mul_u32_u24_e32 v238, 0x3c0, v238
	v_mul_u32_u24_e32 v239, 0x1e0, v239
	v_bitop3_b32 v224, v14, s31, v14 bitop3:0xc
	v_bitop3_b32 v225, v14, s33, v14 bitop3:0xc
	v_bitop3_b32 v226, v14, s34, v14 bitop3:0xc
	v_bitop3_b32 v227, v14, s35, v14 bitop3:0xc
	s_waitcnt lgkmcnt(1)
	v_mfma_f32_32x32x16_bf16 v[80:95], v[6:9], v[140:143], v[80:95]
	v_mul_u32_u24_e32 v224, 0xf00, v224
	v_mul_u32_u24_e32 v225, 0x780, v225
	v_mul_u32_u24_e32 v226, 0x3c0, v226
	v_mul_u32_u24_e32 v227, 0x1e0, v227
	s_waitcnt lgkmcnt(0)
	v_mfma_f32_32x32x16_bf16 v[96:111], v[10:13], v[140:143], v[96:111]
	ds_read_b128 v[6:9], v200 offset:6144
	ds_read_b128 v[10:13], v200 offset:6656
	s_xor_b64 s[4:5], s[20:21], -1
	s_waitcnt lgkmcnt(1)
	v_mfma_f32_32x32x16_bf16 v[80:95], v[6:9], v[148:151], v[80:95]
	s_waitcnt lgkmcnt(0)
	v_mfma_f32_32x32x16_bf16 v[96:111], v[10:13], v[148:151], v[96:111]
	v_mfma_f32_32x32x16_bf16 v[80:95], v[112:115], v[228:231], v[80:95]
	v_mfma_f32_32x32x16_bf16 v[96:111], v[112:115], v[232:235], v[96:111]
	v_mfma_f32_32x32x16_bf16 v[80:95], v[116:119], v[236:239], v[80:95]
	v_mfma_f32_32x32x16_bf16 v[96:111], v[116:119], v[224:227], v[96:111]
	s_nop 15
	s_nop 7
	v_max3_f32 v1, v80, v81, v82
	v_max3_f32 v6, v83, v84, v85
	v_max3_f32 v1, v1, v86, v87
	v_max3_f32 v6, v6, v88, v89
	v_max3_f32 v1, v1, v90, v91
	v_max3_f32 v6, v6, v92, v93
	v_max3_f32 v1, v1, v94, v95
	v_max_f32 v1, v1, v6
	s_nop 0
	v_max3_f32 v7, v96, v97, v98
	v_max3_f32 v6, v99, v100, v101
	v_max3_f32 v7, v7, v102, v103
	v_max3_f32 v6, v6, v104, v105
	v_max3_f32 v7, v7, v106, v107
	v_max3_f32 v6, v6, v108, v109
	v_max3_f32 v7, v7, v110, v111
	v_max3_f32 v7, v7, v6, v1
	s_nop 0
	v_mov_b32_e32 v1, v7
	s_nop 1
	v_permlane32_swap_b32_e32 v7, v1
	v_max_f32_e32 v1, v7, v1
	v_cmp_lt_f32_e64 s[0:1], s36, v1
	s_and_b64 s[10:11], s[0:1], s[4:5]
	v_cmp_lt_f32_e32 vcc, s37, v1
	s_or_b64 s[4:5], vcc, s[10:11]
	s_and_b64 vcc, exec, s[4:5]
	s_cbranch_vccz .LBB0_3764
	v_cndmask_b32_e64 v6, 0, v1, s[4:5]
	v_exp_f32_e64 v1, -v6
	v_add_f32_e32 v171, v171, v6
	s_or_b64 s[0:1], s[20:21], s[0:1]
	v_xor_b32_e32 v64, 0x80000000, v171
	v_cndmask_b32_e64 v8, v1, 1.0, s[10:11]
	s_andn2_b64 s[4:5], s[20:21], exec
	s_and_b64 s[0:1], s[0:1], exec
	v_pk_add_f32 v[80:81], v[80:81], v[6:7] op_sel_hi:[1,0] neg_lo:[0,1] neg_hi:[0,1]
	v_pk_add_f32 v[96:97], v[96:97], v[6:7] op_sel_hi:[1,0] neg_lo:[0,1] neg_hi:[0,1]
	v_pk_add_f32 v[82:83], v[82:83], v[6:7] op_sel_hi:[1,0] neg_lo:[0,1] neg_hi:[0,1]
	v_pk_add_f32 v[98:99], v[98:99], v[6:7] op_sel_hi:[1,0] neg_lo:[0,1] neg_hi:[0,1]
	v_pk_add_f32 v[84:85], v[84:85], v[6:7] op_sel_hi:[1,0] neg_lo:[0,1] neg_hi:[0,1]
	v_pk_add_f32 v[100:101], v[100:101], v[6:7] op_sel_hi:[1,0] neg_lo:[0,1] neg_hi:[0,1]
	v_pk_add_f32 v[86:87], v[86:87], v[6:7] op_sel_hi:[1,0] neg_lo:[0,1] neg_hi:[0,1]
	v_pk_add_f32 v[102:103], v[102:103], v[6:7] op_sel_hi:[1,0] neg_lo:[0,1] neg_hi:[0,1]
	v_pk_add_f32 v[88:89], v[88:89], v[6:7] op_sel_hi:[1,0] neg_lo:[0,1] neg_hi:[0,1]
	v_pk_add_f32 v[104:105], v[104:105], v[6:7] op_sel_hi:[1,0] neg_lo:[0,1] neg_hi:[0,1]
	v_pk_add_f32 v[90:91], v[90:91], v[6:7] op_sel_hi:[1,0] neg_lo:[0,1] neg_hi:[0,1]
	v_pk_add_f32 v[106:107], v[106:107], v[6:7] op_sel_hi:[1,0] neg_lo:[0,1] neg_hi:[0,1]
	v_pk_add_f32 v[92:93], v[92:93], v[6:7] op_sel_hi:[1,0] neg_lo:[0,1] neg_hi:[0,1]
	v_pk_add_f32 v[108:109], v[108:109], v[6:7] op_sel_hi:[1,0] neg_lo:[0,1] neg_hi:[0,1]
	v_pk_add_f32 v[94:95], v[94:95], v[6:7] op_sel_hi:[1,0] neg_lo:[0,1] neg_hi:[0,1]
	v_pk_add_f32 v[110:111], v[110:111], v[6:7] op_sel_hi:[1,0] neg_lo:[0,1] neg_hi:[0,1]
	v_mov_b32_e32 v65, v64
	v_mov_b32_e32 v66, v64
	v_mov_b32_e32 v67, v64
	v_mov_b32_e32 v68, v64
	v_mov_b32_e32 v69, v64
	v_mov_b32_e32 v70, v64
	v_mov_b32_e32 v71, v64
	v_mov_b32_e32 v72, v64
	v_mov_b32_e32 v73, v64
	v_mov_b32_e32 v74, v64
	v_mov_b32_e32 v75, v64
	v_mov_b32_e32 v76, v64
	v_mov_b32_e32 v77, v64
	v_mov_b32_e32 v78, v64
	v_mov_b32_e32 v79, v64
	v_pk_mul_f32 v[30:31], v[30:31], v[8:9] op_sel_hi:[1,0]
	v_pk_mul_f32 v[28:29], v[28:29], v[8:9] op_sel_hi:[1,0]
	v_pk_mul_f32 v[26:27], v[26:27], v[8:9] op_sel_hi:[1,0]
	v_pk_mul_f32 v[24:25], v[24:25], v[8:9] op_sel_hi:[1,0]
	v_pk_mul_f32 v[22:23], v[22:23], v[8:9] op_sel_hi:[1,0]
	v_pk_mul_f32 v[20:21], v[20:21], v[8:9] op_sel_hi:[1,0]
	v_pk_mul_f32 v[18:19], v[18:19], v[8:9] op_sel_hi:[1,0]
	v_pk_mul_f32 v[16:17], v[16:17], v[8:9] op_sel_hi:[1,0]
	v_pk_mul_f32 v[46:47], v[46:47], v[8:9] op_sel_hi:[1,0]
	v_pk_mul_f32 v[44:45], v[44:45], v[8:9] op_sel_hi:[1,0]
	v_pk_mul_f32 v[42:43], v[42:43], v[8:9] op_sel_hi:[1,0]
	v_pk_mul_f32 v[40:41], v[40:41], v[8:9] op_sel_hi:[1,0]
	v_pk_mul_f32 v[38:39], v[38:39], v[8:9] op_sel_hi:[1,0]
	v_pk_mul_f32 v[36:37], v[36:37], v[8:9] op_sel_hi:[1,0]
	v_pk_mul_f32 v[34:35], v[34:35], v[8:9] op_sel_hi:[1,0]
	v_pk_mul_f32 v[32:33], v[32:33], v[8:9] op_sel_hi:[1,0]
	v_pk_mul_f32 v[62:63], v[62:63], v[8:9] op_sel_hi:[1,0]
	v_pk_mul_f32 v[60:61], v[60:61], v[8:9] op_sel_hi:[1,0]
	v_pk_mul_f32 v[58:59], v[58:59], v[8:9] op_sel_hi:[1,0]
	v_pk_mul_f32 v[56:57], v[56:57], v[8:9] op_sel_hi:[1,0]
	v_pk_mul_f32 v[54:55], v[54:55], v[8:9] op_sel_hi:[1,0]
	v_pk_mul_f32 v[52:53], v[52:53], v[8:9] op_sel_hi:[1,0]
	v_pk_mul_f32 v[50:51], v[50:51], v[8:9] op_sel_hi:[1,0]
	v_pk_mul_f32 v[48:49], v[48:49], v[8:9] op_sel_hi:[1,0]
	s_or_b64 s[20:21], s[4:5], s[0:1]
.LBB0_3764:
	ds_read_b64_tr_b16 v[202:203], v157 offset:8192
	ds_read_b64_tr_b16 v[204:205], v157 offset:8704
	ds_read_b64_tr_b16 v[206:207], v157 offset:12288
	ds_read_b64_tr_b16 v[208:209], v157 offset:12800
	v_exp_f32_e32 v80, v80
	v_exp_f32_e32 v81, v81
	v_exp_f32_e32 v82, v82
	v_exp_f32_e32 v83, v83
	v_exp_f32_e32 v84, v84
	v_exp_f32_e32 v85, v85
	v_exp_f32_e32 v86, v86
	v_exp_f32_e32 v87, v87
	v_cvt_pk_bf16_f32 v6, v80, v81
	v_cvt_pk_bf16_f32 v7, v82, v83
	v_cvt_pk_bf16_f32 v8, v84, v85
	v_cvt_pk_bf16_f32 v9, v86, v87
	ds_read_b64_tr_b16 v[210:211], v157 offset:9216
	ds_read_b64_tr_b16 v[212:213], v157 offset:9728
	ds_read_b64_tr_b16 v[214:215], v157 offset:13312
	ds_read_b64_tr_b16 v[216:217], v157 offset:13824
	s_waitcnt lgkmcnt(4)
	v_mfma_f32_32x32x16_bf16 v[16:31], v[202:205], v[6:9], v[16:31]
	v_exp_f32_e32 v88, v88
	v_exp_f32_e32 v89, v89
	v_exp_f32_e32 v90, v90
	v_mfma_f32_32x32x16_bf16 v[32:47], v[206:209], v[6:9], v[32:47]
	v_exp_f32_e32 v91, v91
	v_exp_f32_e32 v92, v92
	v_exp_f32_e32 v93, v93
	v_mfma_f32_32x32x16_bf16 v[48:63], v[120:123], v[6:9], v[48:63]
	v_exp_f32_e32 v94, v94
	v_exp_f32_e32 v95, v95
	v_cvt_pk_bf16_f32 v10, v88, v89
	v_cvt_pk_bf16_f32 v11, v90, v91
	v_cvt_pk_bf16_f32 v12, v92, v93
	v_cvt_pk_bf16_f32 v13, v94, v95
	ds_read_b64_tr_b16 v[202:203], v157 offset:10240
	ds_read_b64_tr_b16 v[204:205], v157 offset:10752
	ds_read_b64_tr_b16 v[206:207], v157 offset:14336
	ds_read_b64_tr_b16 v[208:209], v157 offset:14848
	s_waitcnt lgkmcnt(4)
	v_mfma_f32_32x32x16_bf16 v[16:31], v[210:213], v[10:13], v[16:31]
	v_exp_f32_e32 v96, v96
	v_exp_f32_e32 v97, v97
	v_exp_f32_e32 v98, v98
	v_mfma_f32_32x32x16_bf16 v[32:47], v[214:217], v[10:13], v[32:47]
	v_exp_f32_e32 v99, v99
	v_exp_f32_e32 v100, v100
	v_exp_f32_e32 v101, v101
	v_mfma_f32_32x32x16_bf16 v[48:63], v[120:123], v[10:13], v[48:63]
	v_exp_f32_e32 v102, v102
	v_exp_f32_e32 v103, v103
	v_cvt_pk_bf16_f32 v228, v96, v97
	v_cvt_pk_bf16_f32 v229, v98, v99
	v_cvt_pk_bf16_f32 v230, v100, v101
	v_cvt_pk_bf16_f32 v231, v102, v103
	ds_read_b64_tr_b16 v[210:211], v157 offset:11264
	ds_read_b64_tr_b16 v[212:213], v157 offset:11776
	ds_read_b64_tr_b16 v[214:215], v157 offset:15360
	ds_read_b64_tr_b16 v[216:217], v157 offset:15872
	s_waitcnt lgkmcnt(4)
	v_mfma_f32_32x32x16_bf16 v[16:31], v[202:205], v[228:231], v[16:31]
	v_exp_f32_e32 v104, v104
	v_exp_f32_e32 v105, v105
	v_exp_f32_e32 v106, v106
	v_mfma_f32_32x32x16_bf16 v[32:47], v[206:209], v[228:231], v[32:47]
	v_exp_f32_e32 v107, v107
	v_exp_f32_e32 v108, v108
	v_exp_f32_e32 v109, v109
	v_mfma_f32_32x32x16_bf16 v[48:63], v[120:123], v[228:231], v[48:63]
	v_exp_f32_e32 v110, v110
	v_exp_f32_e32 v111, v111
	v_cvt_pk_bf16_f32 v232, v104, v105
	v_cvt_pk_bf16_f32 v233, v106, v107
	v_cvt_pk_bf16_f32 v234, v108, v109
	v_cvt_pk_bf16_f32 v235, v110, v111
	s_waitcnt lgkmcnt(0)
	s_nop 0
	v_mfma_f32_32x32x16_bf16 v[16:31], v[210:213], v[232:235], v[16:31]
	v_mfma_f32_32x32x16_bf16 v[32:47], v[214:217], v[232:235], v[32:47]
	v_mfma_f32_32x32x16_bf16 v[48:63], v[120:123], v[232:235], v[48:63]
.LBB0_3765:
	s_cmp_ge_u32 s51, s47
	s_cbranch_scc1 .LBB0_3770
	ds_read_b128 v[6:9], v200 offset:16384
	ds_read_b128 v[10:13], v200 offset:16896
	v_lshrrev_b32_e32 v1, v160, v154
	v_lshrrev_b32_e32 v14, v160, v155
	v_bitop3_b32 v228, v1, s27, v1 bitop3:0xc
	v_bitop3_b32 v229, v1, s28, v1 bitop3:0xc
	v_bitop3_b32 v230, v1, s29, v1 bitop3:0xc
	v_bitop3_b32 v231, v1, s30, v1 bitop3:0xc
	s_waitcnt lgkmcnt(1)
	v_mfma_f32_32x32x16_bf16 v[80:95], v[6:9], v[144:147], v[64:79]
	v_mul_u32_u24_e32 v228, 0xf000, v228
	v_mul_u32_u24_e32 v229, 0x7800, v229
	v_mul_u32_u24_e32 v230, 0x3c00, v230
	v_mul_u32_u24_e32 v231, 0x1e00, v231
	s_waitcnt lgkmcnt(0)
	v_mfma_f32_32x32x16_bf16 v[96:111], v[10:13], v[144:147], v[64:79]
	ds_read_b128 v[6:9], v200 offset:18432
	ds_read_b128 v[10:13], v200 offset:18944
	v_bitop3_b32 v232, v14, s27, v14 bitop3:0xc
	v_bitop3_b32 v233, v14, s28, v14 bitop3:0xc
	v_bitop3_b32 v234, v14, s29, v14 bitop3:0xc
	v_bitop3_b32 v235, v14, s30, v14 bitop3:0xc
	v_mul_u32_u24_e32 v232, 0xf000, v232
	v_mul_u32_u24_e32 v233, 0x7800, v233
	v_mul_u32_u24_e32 v234, 0x3c00, v234
	v_mul_u32_u24_e32 v235, 0x1e00, v235
	s_waitcnt lgkmcnt(1)
	v_mfma_f32_32x32x16_bf16 v[80:95], v[6:9], v[136:139], v[80:95]
	v_bitop3_b32 v236, v1, s31, v1 bitop3:0xc
	v_bitop3_b32 v237, v1, s33, v1 bitop3:0xc
	v_bitop3_b32 v238, v1, s34, v1 bitop3:0xc
	v_bitop3_b32 v239, v1, s35, v1 bitop3:0xc
	s_waitcnt lgkmcnt(0)
	v_mfma_f32_32x32x16_bf16 v[96:111], v[10:13], v[136:139], v[96:111]
	ds_read_b128 v[6:9], v200 offset:20480
	ds_read_b128 v[10:13], v200 offset:20992
	v_mul_u32_u24_e32 v236, 0xf00, v236
	v_mul_u32_u24_e32 v237, 0x780, v237
	v_mul_u32_u24_e32 v238, 0x3c0, v238
	v_mul_u32_u24_e32 v239, 0x1e0, v239
	v_bitop3_b32 v224, v14, s31, v14 bitop3:0xc
	v_bitop3_b32 v225, v14, s33, v14 bitop3:0xc
	v_bitop3_b32 v226, v14, s34, v14 bitop3:0xc
	v_bitop3_b32 v227, v14, s35, v14 bitop3:0xc
	s_waitcnt lgkmcnt(1)
	v_mfma_f32_32x32x16_bf16 v[80:95], v[6:9], v[140:143], v[80:95]
	v_mul_u32_u24_e32 v224, 0xf00, v224
	v_mul_u32_u24_e32 v225, 0x780, v225
	v_mul_u32_u24_e32 v226, 0x3c0, v226
	v_mul_u32_u24_e32 v227, 0x1e0, v227
	s_waitcnt lgkmcnt(0)
	v_mfma_f32_32x32x16_bf16 v[96:111], v[10:13], v[140:143], v[96:111]
	ds_read_b128 v[6:9], v200 offset:22528
	ds_read_b128 v[10:13], v200 offset:23040
	s_xor_b64 s[4:5], s[20:21], -1
	s_and_b64 vcc, exec, s[4:5]
	s_waitcnt lgkmcnt(1)
	v_mfma_f32_32x32x16_bf16 v[80:95], v[6:9], v[148:151], v[80:95]
	s_waitcnt lgkmcnt(0)
	v_mfma_f32_32x32x16_bf16 v[96:111], v[10:13], v[148:151], v[96:111]
	v_mfma_f32_32x32x16_bf16 v[80:95], v[112:115], v[228:231], v[80:95]
	v_mfma_f32_32x32x16_bf16 v[96:111], v[112:115], v[232:235], v[96:111]
	v_mfma_f32_32x32x16_bf16 v[80:95], v[116:119], v[236:239], v[80:95]
	v_mfma_f32_32x32x16_bf16 v[96:111], v[116:119], v[224:227], v[96:111]
	s_cbranch_vccz .LBB0_3769
	s_nop 15
	s_nop 7
	v_max3_f32 v1, v80, v81, v82
	v_max3_f32 v6, v83, v84, v85
	v_max3_f32 v1, v1, v86, v87
	v_max3_f32 v6, v6, v88, v89
	v_max3_f32 v1, v1, v90, v91
	v_max3_f32 v6, v6, v92, v93
	v_max3_f32 v1, v1, v94, v95
	v_max_f32 v1, v1, v6
	s_nop 0
	v_max3_f32 v7, v96, v97, v98
	v_max3_f32 v6, v99, v100, v101
	v_max3_f32 v7, v7, v102, v103
	v_max3_f32 v6, v6, v104, v105
	v_max3_f32 v7, v7, v106, v107
	v_max3_f32 v6, v6, v108, v109
	v_max3_f32 v7, v7, v110, v111
	v_max3_f32 v7, v7, v6, v1
	s_nop 0
	v_mov_b32_e32 v1, v7
	s_nop 1
	v_permlane32_swap_b32_e32 v7, v1
	v_max_f32_e32 v1, v7, v1
	v_cmp_lt_f32_e64 s[0:1], s36, v1
	s_and_b64 s[10:11], s[0:1], s[4:5]
	v_cmp_lt_f32_e32 vcc, s37, v1
	s_or_b64 s[4:5], vcc, s[10:11]
	s_and_b64 vcc, exec, s[4:5]
	s_cbranch_vccz .LBB0_3769
	v_cndmask_b32_e64 v1, 0, v1, s[4:5]
	v_exp_f32_e64 v6, -v1
	v_add_f32_e32 v171, v171, v1
	s_or_b64 s[0:1], s[20:21], s[0:1]
	v_xor_b32_e32 v64, 0x80000000, v171
	v_cndmask_b32_e64 v6, v6, 1.0, s[10:11]
	s_andn2_b64 s[4:5], s[20:21], exec
	s_and_b64 s[0:1], s[0:1], exec
	v_mov_b32_e32 v65, v64
	v_mov_b32_e32 v66, v64
	v_mov_b32_e32 v67, v64
	v_mov_b32_e32 v68, v64
	v_mov_b32_e32 v69, v64
	v_mov_b32_e32 v70, v64
	v_mov_b32_e32 v71, v64
	v_mov_b32_e32 v72, v64
	v_mov_b32_e32 v73, v64
	v_mov_b32_e32 v74, v64
	v_mov_b32_e32 v75, v64
	v_mov_b32_e32 v76, v64
	v_mov_b32_e32 v77, v64
	v_mov_b32_e32 v78, v64
	v_mov_b32_e32 v79, v64
	v_pk_mul_f32 v[30:31], v[30:31], v[6:7] op_sel_hi:[1,0]
	v_pk_mul_f32 v[28:29], v[28:29], v[6:7] op_sel_hi:[1,0]
	v_pk_mul_f32 v[26:27], v[26:27], v[6:7] op_sel_hi:[1,0]
	v_pk_mul_f32 v[24:25], v[24:25], v[6:7] op_sel_hi:[1,0]
	v_pk_mul_f32 v[22:23], v[22:23], v[6:7] op_sel_hi:[1,0]
	v_pk_mul_f32 v[20:21], v[20:21], v[6:7] op_sel_hi:[1,0]
	v_pk_mul_f32 v[18:19], v[18:19], v[6:7] op_sel_hi:[1,0]
	v_pk_mul_f32 v[16:17], v[16:17], v[6:7] op_sel_hi:[1,0]
	v_pk_mul_f32 v[46:47], v[46:47], v[6:7] op_sel_hi:[1,0]
	v_pk_mul_f32 v[44:45], v[44:45], v[6:7] op_sel_hi:[1,0]
	v_pk_mul_f32 v[42:43], v[42:43], v[6:7] op_sel_hi:[1,0]
	v_pk_mul_f32 v[40:41], v[40:41], v[6:7] op_sel_hi:[1,0]
	v_pk_mul_f32 v[38:39], v[38:39], v[6:7] op_sel_hi:[1,0]
	v_pk_mul_f32 v[36:37], v[36:37], v[6:7] op_sel_hi:[1,0]
	v_pk_mul_f32 v[34:35], v[34:35], v[6:7] op_sel_hi:[1,0]
	v_pk_mul_f32 v[32:33], v[32:33], v[6:7] op_sel_hi:[1,0]
	v_pk_mul_f32 v[62:63], v[62:63], v[6:7] op_sel_hi:[1,0]
	v_pk_mul_f32 v[60:61], v[60:61], v[6:7] op_sel_hi:[1,0]
	v_pk_mul_f32 v[58:59], v[58:59], v[6:7] op_sel_hi:[1,0]
	v_pk_mul_f32 v[56:57], v[56:57], v[6:7] op_sel_hi:[1,0]
	v_pk_mul_f32 v[54:55], v[54:55], v[6:7] op_sel_hi:[1,0]
	v_pk_mul_f32 v[52:53], v[52:53], v[6:7] op_sel_hi:[1,0]
	v_pk_mul_f32 v[50:51], v[50:51], v[6:7] op_sel_hi:[1,0]
	v_pk_mul_f32 v[48:49], v[48:49], v[6:7] op_sel_hi:[1,0]
	v_sub_f32_e32 v95, v95, v1
	v_sub_f32_e32 v94, v94, v1
	v_sub_f32_e32 v93, v93, v1
	v_sub_f32_e32 v92, v92, v1
	v_sub_f32_e32 v91, v91, v1
	v_sub_f32_e32 v90, v90, v1
	v_sub_f32_e32 v89, v89, v1
	v_sub_f32_e32 v88, v88, v1
	v_sub_f32_e32 v87, v87, v1
	v_sub_f32_e32 v86, v86, v1
	v_sub_f32_e32 v85, v85, v1
	v_sub_f32_e32 v84, v84, v1
	v_sub_f32_e32 v83, v83, v1
	v_sub_f32_e32 v82, v82, v1
	v_sub_f32_e32 v81, v81, v1
	v_sub_f32_e32 v80, v80, v1
	v_sub_f32_e32 v111, v111, v1
	v_sub_f32_e32 v110, v110, v1
	v_sub_f32_e32 v109, v109, v1
	v_sub_f32_e32 v108, v108, v1
	v_sub_f32_e32 v107, v107, v1
	v_sub_f32_e32 v106, v106, v1
	v_sub_f32_e32 v105, v105, v1
	v_sub_f32_e32 v104, v104, v1
	v_sub_f32_e32 v103, v103, v1
	v_sub_f32_e32 v102, v102, v1
	v_sub_f32_e32 v101, v101, v1
	v_sub_f32_e32 v100, v100, v1
	v_sub_f32_e32 v99, v99, v1
	v_sub_f32_e32 v98, v98, v1
	v_sub_f32_e32 v97, v97, v1
	v_sub_f32_e32 v96, v96, v1
	s_or_b64 s[20:21], s[4:5], s[0:1]
.LBB0_3769:
	s_nop 8
	ds_read_b64_tr_b16 v[202:203], v157 offset:24576
	ds_read_b64_tr_b16 v[204:205], v157 offset:25088
	ds_read_b64_tr_b16 v[206:207], v157 offset:28672
	ds_read_b64_tr_b16 v[208:209], v157 offset:29184
	v_exp_f32_e32 v80, v80
	v_exp_f32_e32 v81, v81
	v_exp_f32_e32 v82, v82
	v_exp_f32_e32 v83, v83
	v_exp_f32_e32 v84, v84
	v_exp_f32_e32 v85, v85
	v_exp_f32_e32 v86, v86
	v_exp_f32_e32 v87, v87
	v_cvt_pk_bf16_f32 v6, v80, v81
	v_cvt_pk_bf16_f32 v7, v82, v83
	v_cvt_pk_bf16_f32 v8, v84, v85
	v_cvt_pk_bf16_f32 v9, v86, v87
	ds_read_b64_tr_b16 v[210:211], v157 offset:25600
	ds_read_b64_tr_b16 v[212:213], v157 offset:26112
	ds_read_b64_tr_b16 v[214:215], v157 offset:29696
	ds_read_b64_tr_b16 v[216:217], v157 offset:30208
	s_waitcnt lgkmcnt(4)
	v_mfma_f32_32x32x16_bf16 v[16:31], v[202:205], v[6:9], v[16:31]
	v_exp_f32_e32 v88, v88
	v_exp_f32_e32 v89, v89
	v_exp_f32_e32 v90, v90
	v_mfma_f32_32x32x16_bf16 v[32:47], v[206:209], v[6:9], v[32:47]
	v_exp_f32_e32 v91, v91
	v_exp_f32_e32 v92, v92
	v_exp_f32_e32 v93, v93
	v_mfma_f32_32x32x16_bf16 v[48:63], v[120:123], v[6:9], v[48:63]
	v_exp_f32_e32 v94, v94
	v_exp_f32_e32 v95, v95
	v_cvt_pk_bf16_f32 v10, v88, v89
	v_cvt_pk_bf16_f32 v11, v90, v91
	v_cvt_pk_bf16_f32 v12, v92, v93
	v_cvt_pk_bf16_f32 v13, v94, v95
	ds_read_b64_tr_b16 v[202:203], v157 offset:26624
	ds_read_b64_tr_b16 v[204:205], v157 offset:27136
	ds_read_b64_tr_b16 v[206:207], v157 offset:30720
	ds_read_b64_tr_b16 v[208:209], v157 offset:31232
	s_waitcnt lgkmcnt(4)
	v_mfma_f32_32x32x16_bf16 v[16:31], v[210:213], v[10:13], v[16:31]
	v_exp_f32_e32 v96, v96
	v_exp_f32_e32 v97, v97
	v_exp_f32_e32 v98, v98
	v_mfma_f32_32x32x16_bf16 v[32:47], v[214:217], v[10:13], v[32:47]
	v_exp_f32_e32 v99, v99
	v_exp_f32_e32 v100, v100
	v_exp_f32_e32 v101, v101
	v_mfma_f32_32x32x16_bf16 v[48:63], v[120:123], v[10:13], v[48:63]
	v_exp_f32_e32 v102, v102
	v_exp_f32_e32 v103, v103
	v_cvt_pk_bf16_f32 v228, v96, v97
	v_cvt_pk_bf16_f32 v229, v98, v99
	v_cvt_pk_bf16_f32 v230, v100, v101
	v_cvt_pk_bf16_f32 v231, v102, v103
	ds_read_b64_tr_b16 v[210:211], v157 offset:27648
	ds_read_b64_tr_b16 v[212:213], v157 offset:28160
	ds_read_b64_tr_b16 v[214:215], v157 offset:31744
	ds_read_b64_tr_b16 v[216:217], v157 offset:32256
	s_waitcnt lgkmcnt(4)
	v_mfma_f32_32x32x16_bf16 v[16:31], v[202:205], v[228:231], v[16:31]
	v_exp_f32_e32 v104, v104
	v_exp_f32_e32 v105, v105
	v_exp_f32_e32 v106, v106
	v_mfma_f32_32x32x16_bf16 v[32:47], v[206:209], v[228:231], v[32:47]
	v_exp_f32_e32 v107, v107
	v_exp_f32_e32 v108, v108
	v_exp_f32_e32 v109, v109
	v_mfma_f32_32x32x16_bf16 v[48:63], v[120:123], v[228:231], v[48:63]
	v_exp_f32_e32 v110, v110
	v_exp_f32_e32 v111, v111
	v_cvt_pk_bf16_f32 v232, v104, v105
	v_cvt_pk_bf16_f32 v233, v106, v107
	v_cvt_pk_bf16_f32 v234, v108, v109
	v_cvt_pk_bf16_f32 v235, v110, v111
	s_waitcnt lgkmcnt(0)
	s_nop 0
	v_mfma_f32_32x32x16_bf16 v[16:31], v[210:213], v[232:235], v[16:31]
	v_mfma_f32_32x32x16_bf16 v[32:47], v[214:217], v[232:235], v[32:47]
	v_mfma_f32_32x32x16_bf16 v[48:63], v[120:123], v[232:235], v[48:63]

; #define PG8_STAGE(bufoff, gbase, voff) do { _Pragma("unroll") for (int _i = 0; _i < 2; ++_i) \
;         __builtin_amdgcn_global_load_lds((const unsigned*)((const char*)(gbase) + (voff)[_i]), (PG8_LAS unsigned*)(lds + (bufoff) + ldsw + _i * 8192), 16, 0, 0); } while (0)
; #define PG8_LDA(dst, b, h) do { _Pragma("unroll") for (int m = 0; m < 4; ++m) _Pragma("unroll") for (int k = 0; k < 2; ++k) dst[m][k] = *(const PG8_LAS bf16x8*)(lds + PG8_SA(b, h) + aoff + m * 2048 + k * 1024); } while (0)
; #define PG8_LDB(dst, b, h) do { _Pragma("unroll") for (int n = 0; n < 2; ++n) _Pragma("unroll") for (int k = 0; k < 2; ++k) dst[n][k] = *(const PG8_LAS bf16x8*)(lds + PG8_SB(b, h) + boff + n * 2048 + k * 1024); } while (0)
; #define PG8_WAIT_V(n) asm volatile("s_waitcnt vmcnt(" #n ")" ::: "memory")
; #define PG8_WAIT_L(n) asm volatile("s_waitcnt lgkmcnt(" #n ")" ::: "memory")
; #define PG8_BAR __builtin_amdgcn_s_barrier()
; #define PG8_SCHED __builtin_amdgcn_sched_barrier(0)
; template <class Epi, class Sched, bool ALIGN_EPI = false, bool SP2 = false, bool MIDHOOK = false>
; __device__ __forceinline__ void gemm_phase(PG8_LAS unsigned char* lds, const Gemm g, const Sched& S, const Epi& E) {
;     ...
;         for (int t = 0; t < nt; t += 2) {
;             if constexpr (MIDHOOK) { if (t == nt / 2) E.mid(acc, cur, wr, wc, fr, fq); }
;             const bool last = (t == nt - 2);
;             const char* a1 = cA + (size_t)(t + 1) * kstep;
;             const char* a2 = last ? nA : cA + (size_t)(t + 2) * kstep; const char* b2 = last ? nB : cB + (size_t)(t + 2) * kstep;
;             const char* a3 = a2 + kstep; const char* b3 = b2 + kstep;
;             if (last && has_next) S.a_ready(nxt);
;             if constexpr (SP2) {
;             PG8_LDB(B0, 0, 0); PG8_LDB(B1, 0, 1); PG8_SCHED; PG8_LDA(At, 0, 0); PG8_STAGE(PG8_SA(1, 1), a1 + hstep, voffA);
;             PG8_WAIT_V(8); PG8_WAIT_L(0); PG8_BAR; PG8_MMA(0, 0, At, B0); PG8_MMA(0, 1, At, B1); PG8_BAR; PG8_SCHED;
;     ...
; #pragma unroll
;         for (int a = 0; a < 2; ++a)
; #pragma unroll
;             for (int b = 0; b < 2; ++b)
; #pragma unroll
;                 for (int m = 0; m < 4; ++m)
; #pragma unroll
;                     for (int n = 0; n < 2; ++n) acc[a][b][m][n] = (f32x4){0.f, 0.f, 0.f, 0.f};
;         cur = nxt; cA = nA; cB = nB; ++ui;
.LBB0_3840:
	s_ashr_i32 s19, s18, 31
	s_lshl_b64 s[20:21], s[18:19], 19
	s_add_u32 s20, s68, s20
	s_addc_u32 s21, s69, s21
	s_and_b64 s[22:23], s[0:1], exec
	s_cselect_b32 s19, s21, s25
	s_cselect_b32 s46, s20, s24
	s_ashr_i32 s17, s16, 31
	s_lshl_b64 s[22:23], s[16:17], 19
	v_readlane_b32 s30, v243, 24
	v_readlane_b32 s31, v243, 25
	s_add_u32 s22, s30, s22
	s_addc_u32 s23, s31, s23
	s_and_b64 s[30:31], s[0:1], exec
	v_mov_b32_e32 v2, v0
	v_mov_b32_e32 v3, v0
	s_cselect_b32 s17, s23, s29
	s_cselect_b32 s47, s22, s28
	s_add_u32 s48, s28, 0x100
	v_mov_b32_e32 v1, v0
	v_mov_b64_e32 v[6:7], v[2:3]
	v_mov_b64_e32 v[10:11], v[2:3]
	v_mov_b64_e32 v[22:23], v[2:3]
	v_mov_b64_e32 v[26:27], v[2:3]
	v_mov_b64_e32 v[38:39], v[2:3]
	v_mov_b64_e32 v[42:43], v[2:3]
	v_mov_b64_e32 v[54:55], v[2:3]
	v_mov_b64_e32 v[58:59], v[2:3]
	v_mov_b64_e32 v[14:15], v[2:3]
	v_mov_b64_e32 v[18:19], v[2:3]
	v_mov_b64_e32 v[30:31], v[2:3]
	v_mov_b64_e32 v[34:35], v[2:3]
	v_mov_b64_e32 v[46:47], v[2:3]
	v_mov_b64_e32 v[50:51], v[2:3]
	v_mov_b64_e32 v[62:63], v[2:3]
	v_mov_b64_e32 v[66:67], v[2:3]
	v_mov_b64_e32 v[70:71], v[2:3]
	v_mov_b64_e32 v[74:75], v[2:3]
	v_mov_b64_e32 v[86:87], v[2:3]
	v_mov_b64_e32 v[90:91], v[2:3]
	v_mov_b64_e32 v[102:103], v[2:3]
	v_mov_b64_e32 v[106:107], v[2:3]
	v_mov_b64_e32 v[118:119], v[2:3]
	v_mov_b64_e32 v[122:123], v[2:3]
	v_mov_b64_e32 v[78:79], v[2:3]
	v_mov_b64_e32 v[82:83], v[2:3]
	v_mov_b64_e32 v[94:95], v[2:3]
	v_mov_b64_e32 v[98:99], v[2:3]
	v_mov_b64_e32 v[110:111], v[2:3]
	v_mov_b64_e32 v[114:115], v[2:3]
	v_mov_b64_e32 v[126:127], v[2:3]
	v_mov_b64_e32 v[130:131], v[2:3]
	v_lshl_add_u32 v204, s26, 8, v223
	v_lshl_add_u32 v206, s27, 8, v225
	v_lshl_add_u64 v[208:209], s[24:25], 0, v[196:197]
	v_lshl_add_u64 v[210:211], s[24:25], 0, v[198:199]
	s_addc_u32 s49, s29, 0
	s_mov_b32 s50, -2
	s_mov_b64 s[26:27], 0
	v_mov_b64_e32 v[4:5], v[0:1]
	v_mov_b64_e32 v[8:9], v[0:1]
	v_mov_b64_e32 v[20:21], v[0:1]
	v_mov_b64_e32 v[24:25], v[0:1]
	v_mov_b64_e32 v[36:37], v[0:1]
	v_mov_b64_e32 v[40:41], v[0:1]
	v_mov_b64_e32 v[52:53], v[0:1]
	v_mov_b64_e32 v[56:57], v[0:1]
	v_mov_b64_e32 v[12:13], v[0:1]
	v_mov_b64_e32 v[16:17], v[0:1]
	v_mov_b64_e32 v[28:29], v[0:1]
	v_mov_b64_e32 v[32:33], v[0:1]
	v_mov_b64_e32 v[44:45], v[0:1]
	v_mov_b64_e32 v[48:49], v[0:1]
	v_mov_b64_e32 v[60:61], v[0:1]
	v_mov_b64_e32 v[64:65], v[0:1]
	v_mov_b64_e32 v[68:69], v[0:1]
	v_mov_b64_e32 v[72:73], v[0:1]
	v_mov_b64_e32 v[84:85], v[0:1]
	v_mov_b64_e32 v[88:89], v[0:1]
	v_mov_b64_e32 v[100:101], v[0:1]
	v_mov_b64_e32 v[104:105], v[0:1]
	v_mov_b64_e32 v[116:117], v[0:1]
	v_mov_b64_e32 v[120:121], v[0:1]
	v_mov_b64_e32 v[76:77], v[0:1]
	v_mov_b64_e32 v[80:81], v[0:1]
	v_mov_b64_e32 v[92:93], v[0:1]
	v_mov_b64_e32 v[96:97], v[0:1]
	v_mov_b64_e32 v[108:109], v[0:1]
	v_mov_b64_e32 v[112:113], v[0:1]
	v_mov_b64_e32 v[124:125], v[0:1]
	v_mov_b64_e32 v[128:129], v[0:1]
	s_branch .LBB0_3842
	s_nop 0
	s_nop 0
	s_nop 0
	s_nop 0
	s_nop 0
	s_nop 0
	s_nop 0
	s_nop 0
.LBB0_3841:
	v_add_u32_e32 v1, s44, v224
	ds_read_b128 v[132:135], v1
	ds_read_b128 v[136:139], v1 offset:1024
	ds_read_b128 v[140:143], v1 offset:2048
	ds_read_b128 v[144:147], v1 offset:3072
	v_add_u32_e32 v1, s45, v224
	s_add_u32 s28, s24, s26
	ds_read_b128 v[148:151], v1
	ds_read_b128 v[152:155], v1 offset:1024
	ds_read_b128 v[156:159], v1 offset:2048
	ds_read_b128 v[160:163], v1 offset:3072
	s_addc_u32 s29, s25, s27
	s_add_u32 s28, s28, 0x100
	s_addc_u32 s29, s29, 0
	s_add_u32 s51, s48, s26
	s_addc_u32 s52, s49, s27
	s_cmpk_eq_i32 s26, 0x700
	s_cselect_b32 s31, s19, s29
	s_cselect_b32 s30, s46, s28
	s_cselect_b32 s29, s17, s52
	s_cselect_b32 s28, s47, s51
	v_lshl_add_u64 v[2:3], v[208:209], 0, s[26:27]
	s_add_i32 m0, s35, 0xc000
	ds_read_b128 v[164:167], v226
	ds_read_b128 v[168:171], v226 offset:1024
	ds_read_b128 v[172:175], v226 offset:2048
	ds_read_b128 v[176:179], v226 offset:3072
	ds_read_b128 v[180:183], v226 offset:4096
	ds_read_b128 v[184:187], v226 offset:5120
	ds_read_b128 v[212:215], v226 offset:6144
	ds_read_b128 v[216:219], v226 offset:7168
	global_load_lds_dwordx4 v[2:3], off
	v_lshl_add_u64 v[2:3], v[210:211], 0, s[26:27]
	s_add_i32 m0, s35, 0xe000
	s_nop 0
	global_load_lds_dwordx4 v[2:3], off
	s_waitcnt vmcnt(8)
	s_waitcnt lgkmcnt(0)
	s_barrier
	s_setprio 1
	s_waitcnt lgkmcnt(0)
	v_mfma_f32_16x16x32_bf16 v[128:131], v[132:135], v[164:167], v[128:131]
	v_mfma_f32_16x16x32_bf16 v[124:127], v[140:143], v[164:167], v[124:127]
	v_mfma_f32_16x16x32_bf16 v[112:115], v[132:135], v[172:175], v[112:115]
	v_mfma_f32_16x16x32_bf16 v[108:111], v[140:143], v[172:175], v[108:111]
	v_mfma_f32_16x16x32_bf16 v[96:99], v[132:135], v[180:183], v[96:99]
	v_mfma_f32_16x16x32_bf16 v[92:95], v[140:143], v[180:183], v[92:95]
	v_mfma_f32_16x16x32_bf16 v[80:83], v[132:135], v[212:215], v[80:83]
	v_mfma_f32_16x16x32_bf16 v[76:79], v[140:143], v[212:215], v[76:79]
	v_mfma_f32_16x16x32_bf16 v[128:131], v[136:139], v[168:171], v[128:131]
	v_mfma_f32_16x16x32_bf16 v[124:127], v[144:147], v[168:171], v[124:127]
	v_mfma_f32_16x16x32_bf16 v[112:115], v[136:139], v[176:179], v[112:115]
	v_mfma_f32_16x16x32_bf16 v[108:111], v[144:147], v[176:179], v[108:111]
	v_mfma_f32_16x16x32_bf16 v[96:99], v[136:139], v[184:187], v[96:99]
	v_mfma_f32_16x16x32_bf16 v[92:95], v[144:147], v[184:187], v[92:95]
	v_mfma_f32_16x16x32_bf16 v[80:83], v[136:139], v[216:219], v[80:83]
	v_mfma_f32_16x16x32_bf16 v[76:79], v[144:147], v[216:219], v[76:79]
	s_setprio 0
	s_setprio 1
	v_mfma_f32_16x16x32_bf16 v[120:123], v[148:151], v[164:167], v[120:123]
	v_mfma_f32_16x16x32_bf16 v[116:119], v[156:159], v[164:167], v[116:119]
	v_mfma_f32_16x16x32_bf16 v[104:107], v[148:151], v[172:175], v[104:107]
	v_mfma_f32_16x16x32_bf16 v[100:103], v[156:159], v[172:175], v[100:103]
	v_mfma_f32_16x16x32_bf16 v[88:91], v[148:151], v[180:183], v[88:91]
	v_mfma_f32_16x16x32_bf16 v[84:87], v[156:159], v[180:183], v[84:87]
	v_mfma_f32_16x16x32_bf16 v[72:75], v[148:151], v[212:215], v[72:75]
	v_mfma_f32_16x16x32_bf16 v[68:71], v[156:159], v[212:215], v[68:71]
	v_mfma_f32_16x16x32_bf16 v[120:123], v[152:155], v[168:171], v[120:123]
	v_mfma_f32_16x16x32_bf16 v[116:119], v[160:163], v[168:171], v[116:119]
	v_mfma_f32_16x16x32_bf16 v[104:107], v[152:155], v[176:179], v[104:107]
	v_mfma_f32_16x16x32_bf16 v[100:103], v[160:163], v[176:179], v[100:103]
	v_mfma_f32_16x16x32_bf16 v[88:91], v[152:155], v[184:187], v[88:91]
	v_mfma_f32_16x16x32_bf16 v[84:87], v[160:163], v[184:187], v[84:87]
	v_mfma_f32_16x16x32_bf16 v[72:75], v[152:155], v[216:219], v[72:75]
	v_mfma_f32_16x16x32_bf16 v[68:71], v[160:163], v[216:219], v[68:71]
	s_setprio 0
	s_barrier
; #define PG8_STAGE(bufoff, gbase, voff) do { _Pragma("unroll") for (int _i = 0; _i < 2; ++_i) \
;         __builtin_amdgcn_global_load_lds((const unsigned*)((const char*)(gbase) + (voff)[_i]), (PG8_LAS unsigned*)(lds + (bufoff) + ldsw + _i * 8192), 16, 0, 0); } while (0)
; #define PG8_LDA(dst, b, h) do { _Pragma("unroll") for (int m = 0; m < 4; ++m) _Pragma("unroll") for (int k = 0; k < 2; ++k) dst[m][k] = *(const PG8_LAS bf16x8*)(lds + PG8_SA(b, h) + aoff + m * 2048 + k * 1024); } while (0)
; #define PG8_LDB(dst, b, h) do { _Pragma("unroll") for (int n = 0; n < 2; ++n) _Pragma("unroll") for (int k = 0; k < 2; ++k) dst[n][k] = *(const PG8_LAS bf16x8*)(lds + PG8_SB(b, h) + boff + n * 2048 + k * 1024); } while (0)
; #define PG8_MMA(ai, bj, At, Bt) do { __builtin_amdgcn_s_setprio(1); _Pragma("unroll") for (int m = 0; m < 4; ++m) _Pragma("unroll") for (int n = 0; n < 2; ++n) _Pragma("unroll") for (int k = 0; k < 2; ++k) \
;         acc[ai][bj][m][n] = __builtin_amdgcn_mfma_f32_16x16x32_bf16(Bt[n][k], At[m][k], acc[ai][bj][m][n], 0, 0, 0); __builtin_amdgcn_s_setprio(0); } while (0)
; #define PG8_WAIT_V(n) asm volatile("s_waitcnt vmcnt(" #n ")" ::: "memory")
; #define PG8_WAIT_L(n) asm volatile("s_waitcnt lgkmcnt(" #n ")" ::: "memory")
; #define PG8_BAR __builtin_amdgcn_s_barrier()
; #define PG8_SCHED __builtin_amdgcn_sched_barrier(0)
; template <class Epi, class Sched, bool ALIGN_EPI = false, bool SP2 = false, bool MIDHOOK = false>
; __device__ __forceinline__ void gemm_phase(PG8_LAS unsigned char* lds, const Gemm g, const Sched& S, const Epi& E) {
;     ...
;             PG8_WAIT_V(8); PG8_WAIT_L(0); PG8_BAR; PG8_MMA(0, 0, At, B0); PG8_MMA(0, 1, At, B1); PG8_BAR; PG8_SCHED;
;             PG8_LDA(At, 0, 1); PG8_STAGE(PG8_SB(0, 0), b2, voffB); PG8_STAGE(PG8_SB(0, 1), b2 + hstep, voffB); PG8_STAGE(PG8_SA(0, 0), a2, voffA);
;             PG8_WAIT_V(8); PG8_WAIT_L(0); PG8_BAR; PG8_MMA(1, 0, At, B0); PG8_MMA(1, 1, At, B1); PG8_BAR; PG8_SCHED;
;             PG8_LDB(B0, 1, 0); PG8_LDB(B1, 1, 1); PG8_SCHED; PG8_LDA(At, 1, 0); PG8_STAGE(PG8_SA(0, 1), a2 + hstep, voffA);
;             PG8_WAIT_V(8); PG8_WAIT_L(0); PG8_BAR; PG8_MMA(0, 0, At, B0); PG8_MMA(0, 1, At, B1); PG8_BAR; PG8_SCHED;
	s_add_i32 s51, s44, s34
	v_lshl_add_u64 v[228:229], s[28:29], 0, v[190:191]
	s_mov_b32 m0, s51
	ds_read_b128 v[164:167], v226 offset:16384
	ds_read_b128 v[168:171], v226 offset:17408
	ds_read_b128 v[172:175], v226 offset:18432
	ds_read_b128 v[176:179], v226 offset:19456
	ds_read_b128 v[180:183], v226 offset:20480
	ds_read_b128 v[184:187], v226 offset:21504
	ds_read_b128 v[212:215], v226 offset:22528
	ds_read_b128 v[216:219], v226 offset:23552
	global_load_lds_dwordx4 v[228:229], off
	s_add_i32 m0, s51, 0x2000
	s_add_u32 s52, s28, 0x40000
	v_lshl_add_u64 v[230:231], s[28:29], 0, v[194:195]
	s_addc_u32 s53, s29, 0
	s_add_i32 s51, s45, s34
	global_load_lds_dwordx4 v[230:231], off
	v_lshl_add_u64 v[2:3], s[52:53], 0, v[190:191]
	s_mov_b32 m0, s51
	v_lshl_add_u64 v[232:233], s[30:31], 0, v[188:189]
	global_load_lds_dwordx4 v[2:3], off
	v_lshl_add_u64 v[2:3], s[52:53], 0, v[194:195]
	s_add_i32 m0, s51, 0x2000
	v_lshl_add_u64 v[234:235], s[30:31], 0, v[192:193]
	global_load_lds_dwordx4 v[2:3], off
	s_mov_b32 m0, s35
	s_nop 0
	global_load_lds_dwordx4 v[232:233], off
	s_mov_b32 m0, s36
	s_nop 0
	global_load_lds_dwordx4 v[234:235], off
	s_waitcnt vmcnt(8)
	s_waitcnt lgkmcnt(0)
	s_barrier
	s_setprio 1
	s_waitcnt lgkmcnt(0)
	v_mfma_f32_16x16x32_bf16 v[64:67], v[132:135], v[164:167], v[64:67]
	v_mfma_f32_16x16x32_bf16 v[60:63], v[140:143], v[164:167], v[60:63]
	v_mfma_f32_16x16x32_bf16 v[48:51], v[132:135], v[172:175], v[48:51]
	v_mfma_f32_16x16x32_bf16 v[44:47], v[140:143], v[172:175], v[44:47]
	v_mfma_f32_16x16x32_bf16 v[32:35], v[132:135], v[180:183], v[32:35]
	v_mfma_f32_16x16x32_bf16 v[28:31], v[140:143], v[180:183], v[28:31]
	v_mfma_f32_16x16x32_bf16 v[16:19], v[132:135], v[212:215], v[16:19]
	v_mfma_f32_16x16x32_bf16 v[12:15], v[140:143], v[212:215], v[12:15]
	v_mfma_f32_16x16x32_bf16 v[64:67], v[136:139], v[168:171], v[64:67]
	v_mfma_f32_16x16x32_bf16 v[60:63], v[144:147], v[168:171], v[60:63]
	v_mfma_f32_16x16x32_bf16 v[48:51], v[136:139], v[176:179], v[48:51]
	v_mfma_f32_16x16x32_bf16 v[44:47], v[144:147], v[176:179], v[44:47]
	v_mfma_f32_16x16x32_bf16 v[32:35], v[136:139], v[184:187], v[32:35]
	v_mfma_f32_16x16x32_bf16 v[28:31], v[144:147], v[184:187], v[28:31]
	v_mfma_f32_16x16x32_bf16 v[16:19], v[136:139], v[216:219], v[16:19]
	v_mfma_f32_16x16x32_bf16 v[12:15], v[144:147], v[216:219], v[12:15]
	s_setprio 0
	s_setprio 1
	v_mfma_f32_16x16x32_bf16 v[56:59], v[148:151], v[164:167], v[56:59]
	v_mfma_f32_16x16x32_bf16 v[52:55], v[156:159], v[164:167], v[52:55]
	v_mfma_f32_16x16x32_bf16 v[40:43], v[148:151], v[172:175], v[40:43]
	v_mfma_f32_16x16x32_bf16 v[36:39], v[156:159], v[172:175], v[36:39]
	v_mfma_f32_16x16x32_bf16 v[24:27], v[148:151], v[180:183], v[24:27]
	v_mfma_f32_16x16x32_bf16 v[20:23], v[156:159], v[180:183], v[20:23]
	v_mfma_f32_16x16x32_bf16 v[8:11], v[148:151], v[212:215], v[8:11]
	v_mfma_f32_16x16x32_bf16 v[2:5], v[156:159], v[212:215], v[4:7]
	v_mfma_f32_16x16x32_bf16 v[56:59], v[152:155], v[168:171], v[56:59]
	v_mfma_f32_16x16x32_bf16 v[52:55], v[160:163], v[168:171], v[52:55]
	v_mfma_f32_16x16x32_bf16 v[40:43], v[152:155], v[176:179], v[40:43]
	v_mfma_f32_16x16x32_bf16 v[36:39], v[160:163], v[176:179], v[36:39]
	v_mfma_f32_16x16x32_bf16 v[24:27], v[152:155], v[184:187], v[24:27]
	v_mfma_f32_16x16x32_bf16 v[20:23], v[160:163], v[184:187], v[20:23]
	v_mfma_f32_16x16x32_bf16 v[8:11], v[152:155], v[216:219], v[8:11]
	v_mfma_f32_16x16x32_bf16 v[2:5], v[160:163], v[216:219], v[2:5]
	s_setprio 0
	s_barrier
	s_add_i32 s51, 0, 0x18000
	v_add_u32_e32 v1, s51, v224
	s_add_i32 s52, 0, 0x1c000
	ds_read_b128 v[132:135], v1
	ds_read_b128 v[136:139], v1 offset:1024
	ds_read_b128 v[140:143], v1 offset:2048
	ds_read_b128 v[144:147], v1 offset:3072
	v_add_u32_e32 v1, s52, v224
	ds_read_b128 v[148:151], v1
	ds_read_b128 v[152:155], v1 offset:1024
	ds_read_b128 v[156:159], v1 offset:2048
	ds_read_b128 v[160:163], v1 offset:3072
	s_add_u32 s30, s30, 0x40000
	s_addc_u32 s31, s31, 0
	s_mov_b32 m0, s37
	v_lshl_add_u64 v[6:7], s[30:31], 0, v[188:189]
	ds_read_b128 v[164:167], v226 offset:32768
	ds_read_b128 v[168:171], v226 offset:33792
	ds_read_b128 v[172:175], v226 offset:34816
	ds_read_b128 v[176:179], v226 offset:35840
	ds_read_b128 v[180:183], v226 offset:36864
	ds_read_b128 v[184:187], v226 offset:37888
	ds_read_b128 v[212:215], v226 offset:38912
	ds_read_b128 v[216:219], v226 offset:39936
	global_load_lds_dwordx4 v[6:7], off
	v_lshl_add_u64 v[6:7], s[30:31], 0, v[192:193]
	s_mov_b32 m0, s38
	s_nop 0
	global_load_lds_dwordx4 v[6:7], off
	s_waitcnt vmcnt(8)
	s_waitcnt lgkmcnt(0)
	s_barrier
; #define PG8_STAGE(bufoff, gbase, voff) do { _Pragma("unroll") for (int _i = 0; _i < 2; ++_i) \
;         __builtin_amdgcn_global_load_lds((const unsigned*)((const char*)(gbase) + (voff)[_i]), (PG8_LAS unsigned*)(lds + (bufoff) + ldsw + _i * 8192), 16, 0, 0); } while (0)
; #define PG8_LDA(dst, b, h) do { _Pragma("unroll") for (int m = 0; m < 4; ++m) _Pragma("unroll") for (int k = 0; k < 2; ++k) dst[m][k] = *(const PG8_LAS bf16x8*)(lds + PG8_SA(b, h) + aoff + m * 2048 + k * 1024); } while (0)
; #define PG8_MMA(ai, bj, At, Bt) do { __builtin_amdgcn_s_setprio(1); _Pragma("unroll") for (int m = 0; m < 4; ++m) _Pragma("unroll") for (int n = 0; n < 2; ++n) _Pragma("unroll") for (int k = 0; k < 2; ++k) \
;         acc[ai][bj][m][n] = __builtin_amdgcn_mfma_f32_16x16x32_bf16(Bt[n][k], At[m][k], acc[ai][bj][m][n], 0, 0, 0); __builtin_amdgcn_s_setprio(0); } while (0)
; #define PG8_WAIT_V(n) asm volatile("s_waitcnt vmcnt(" #n ")" ::: "memory")
; #define PG8_WAIT_L(n) asm volatile("s_waitcnt lgkmcnt(" #n ")" ::: "memory")
; #define PG8_BAR __builtin_amdgcn_s_barrier()
; #define PG8_SCHED __builtin_amdgcn_sched_barrier(0)
; template <class Epi, class Sched, bool ALIGN_EPI = false, bool SP2 = false, bool MIDHOOK = false>
; __device__ __forceinline__ void gemm_phase(PG8_LAS unsigned char* lds, const Gemm g, const Sched& S, const Epi& E) {
;     ...
;             PG8_WAIT_V(8); PG8_WAIT_L(0); PG8_BAR; PG8_MMA(0, 0, At, B0); PG8_MMA(0, 1, At, B1); PG8_BAR; PG8_SCHED;
;             PG8_LDA(At, 1, 1); PG8_STAGE(PG8_SB(1, 0), b3, voffB); PG8_STAGE(PG8_SB(1, 1), b3 + hstep, voffB); PG8_STAGE(PG8_SA(1, 0), a3, voffA);
;             PG8_WAIT_V(8); PG8_WAIT_L(0); PG8_BAR; PG8_MMA(1, 0, At, B0); PG8_MMA(1, 1, At, B1); PG8_BAR; PG8_SCHED;
	s_setprio 1
	s_waitcnt lgkmcnt(0)
	v_mfma_f32_16x16x32_bf16 v[128:131], v[132:135], v[164:167], v[128:131]
	v_mfma_f32_16x16x32_bf16 v[124:127], v[140:143], v[164:167], v[124:127]
	v_mfma_f32_16x16x32_bf16 v[112:115], v[132:135], v[172:175], v[112:115]
	v_mfma_f32_16x16x32_bf16 v[108:111], v[140:143], v[172:175], v[108:111]
	v_mfma_f32_16x16x32_bf16 v[96:99], v[132:135], v[180:183], v[96:99]
	v_mfma_f32_16x16x32_bf16 v[92:95], v[140:143], v[180:183], v[92:95]
	v_mfma_f32_16x16x32_bf16 v[80:83], v[132:135], v[212:215], v[80:83]
	v_mfma_f32_16x16x32_bf16 v[76:79], v[140:143], v[212:215], v[76:79]
	v_mfma_f32_16x16x32_bf16 v[128:131], v[136:139], v[168:171], v[128:131]
	v_mfma_f32_16x16x32_bf16 v[124:127], v[144:147], v[168:171], v[124:127]
	v_mfma_f32_16x16x32_bf16 v[112:115], v[136:139], v[176:179], v[112:115]
	v_mfma_f32_16x16x32_bf16 v[108:111], v[144:147], v[176:179], v[108:111]
	v_mfma_f32_16x16x32_bf16 v[96:99], v[136:139], v[184:187], v[96:99]
	v_mfma_f32_16x16x32_bf16 v[92:95], v[144:147], v[184:187], v[92:95]
	v_mfma_f32_16x16x32_bf16 v[80:83], v[136:139], v[216:219], v[80:83]
	v_mfma_f32_16x16x32_bf16 v[76:79], v[144:147], v[216:219], v[76:79]
	s_setprio 0
	s_setprio 1
	v_mfma_f32_16x16x32_bf16 v[120:123], v[148:151], v[164:167], v[120:123]
	v_mfma_f32_16x16x32_bf16 v[116:119], v[156:159], v[164:167], v[116:119]
	v_mfma_f32_16x16x32_bf16 v[104:107], v[148:151], v[172:175], v[104:107]
	v_mfma_f32_16x16x32_bf16 v[100:103], v[156:159], v[172:175], v[100:103]
	v_mfma_f32_16x16x32_bf16 v[88:91], v[148:151], v[180:183], v[88:91]
	v_mfma_f32_16x16x32_bf16 v[84:87], v[156:159], v[180:183], v[84:87]
	v_mfma_f32_16x16x32_bf16 v[72:75], v[148:151], v[212:215], v[72:75]
	v_mfma_f32_16x16x32_bf16 v[68:71], v[156:159], v[212:215], v[68:71]
	v_mfma_f32_16x16x32_bf16 v[120:123], v[152:155], v[168:171], v[120:123]
	v_mfma_f32_16x16x32_bf16 v[116:119], v[160:163], v[168:171], v[116:119]
	v_mfma_f32_16x16x32_bf16 v[104:107], v[152:155], v[176:179], v[104:107]
	v_mfma_f32_16x16x32_bf16 v[100:103], v[160:163], v[176:179], v[100:103]
	v_mfma_f32_16x16x32_bf16 v[88:91], v[152:155], v[184:187], v[88:91]
	v_mfma_f32_16x16x32_bf16 v[84:87], v[160:163], v[184:187], v[84:87]
	v_mfma_f32_16x16x32_bf16 v[72:75], v[152:155], v[216:219], v[72:75]
	v_mfma_f32_16x16x32_bf16 v[68:71], v[160:163], v[216:219], v[68:71]
	s_setprio 0
	s_barrier
	s_add_i32 s30, s51, s34
	v_lshl_add_u64 v[6:7], v[228:229], 0, s[10:11]
	s_mov_b32 m0, s30
	ds_read_b128 v[164:167], v226 offset:49152
	ds_read_b128 v[168:171], v226 offset:50176
	ds_read_b128 v[172:175], v226 offset:51200
	ds_read_b128 v[176:179], v226 offset:52224
	ds_read_b128 v[180:183], v226 offset:53248
	ds_read_b128 v[184:187], v226 offset:54272
	ds_read_b128 v[212:215], v226 offset:55296
	ds_read_b128 v[216:219], v226 offset:56320
	global_load_lds_dwordx4 v[6:7], off
	s_add_i32 m0, s30, 0x2000
	s_add_u32 s28, s28, 0x40080
	v_lshl_add_u64 v[6:7], v[230:231], 0, s[10:11]
	s_addc_u32 s29, s29, 0
	s_add_i32 s30, s52, s34
	global_load_lds_dwordx4 v[6:7], off
	v_lshl_add_u64 v[6:7], s[28:29], 0, v[190:191]
	s_mov_b32 m0, s30
	s_nop 0
	global_load_lds_dwordx4 v[6:7], off
	v_lshl_add_u64 v[6:7], s[28:29], 0, v[194:195]
	s_add_i32 m0, s30, 0x2000
	s_nop 0
	global_load_lds_dwordx4 v[6:7], off
	v_lshl_add_u64 v[6:7], v[232:233], 0, s[10:11]
	s_mov_b32 m0, s40
	s_nop 0
	global_load_lds_dwordx4 v[6:7], off
	v_lshl_add_u64 v[6:7], v[234:235], 0, s[10:11]
	s_mov_b32 m0, s41
	s_nop 0
	global_load_lds_dwordx4 v[6:7], off
	s_waitcnt vmcnt(8)
	s_waitcnt lgkmcnt(0)
	s_barrier
	s_setprio 1
	s_waitcnt lgkmcnt(0)
	v_mfma_f32_16x16x32_bf16 v[64:67], v[132:135], v[164:167], v[64:67]
	v_mfma_f32_16x16x32_bf16 v[60:63], v[140:143], v[164:167], v[60:63]
	v_mfma_f32_16x16x32_bf16 v[48:51], v[132:135], v[172:175], v[48:51]
	v_mfma_f32_16x16x32_bf16 v[44:47], v[140:143], v[172:175], v[44:47]
	v_mfma_f32_16x16x32_bf16 v[32:35], v[132:135], v[180:183], v[32:35]
	v_mfma_f32_16x16x32_bf16 v[28:31], v[140:143], v[180:183], v[28:31]
	v_mfma_f32_16x16x32_bf16 v[16:19], v[132:135], v[212:215], v[16:19]
	v_mfma_f32_16x16x32_bf16 v[12:15], v[140:143], v[212:215], v[12:15]
	v_mfma_f32_16x16x32_bf16 v[64:67], v[136:139], v[168:171], v[64:67]
	v_mfma_f32_16x16x32_bf16 v[60:63], v[144:147], v[168:171], v[60:63]
	v_mfma_f32_16x16x32_bf16 v[48:51], v[136:139], v[176:179], v[48:51]
	v_mfma_f32_16x16x32_bf16 v[44:47], v[144:147], v[176:179], v[44:47]
	v_mfma_f32_16x16x32_bf16 v[32:35], v[136:139], v[184:187], v[32:35]
	v_mfma_f32_16x16x32_bf16 v[28:31], v[144:147], v[184:187], v[28:31]
	v_mfma_f32_16x16x32_bf16 v[16:19], v[136:139], v[216:219], v[16:19]
	v_mfma_f32_16x16x32_bf16 v[12:15], v[144:147], v[216:219], v[12:15]
	s_setprio 0
	s_setprio 1
	v_mfma_f32_16x16x32_bf16 v[56:59], v[148:151], v[164:167], v[56:59]
	v_mfma_f32_16x16x32_bf16 v[52:55], v[156:159], v[164:167], v[52:55]
	v_mfma_f32_16x16x32_bf16 v[40:43], v[148:151], v[172:175], v[40:43]
	v_mfma_f32_16x16x32_bf16 v[36:39], v[156:159], v[172:175], v[36:39]
	v_mfma_f32_16x16x32_bf16 v[24:27], v[148:151], v[180:183], v[24:27]
	v_mfma_f32_16x16x32_bf16 v[20:23], v[156:159], v[180:183], v[20:23]
	v_mfma_f32_16x16x32_bf16 v[6:9], v[148:151], v[212:215], v[8:11]
	v_mfma_f32_16x16x32_bf16 v[2:5], v[156:159], v[212:215], v[2:5]
	v_mfma_f32_16x16x32_bf16 v[56:59], v[152:155], v[168:171], v[56:59]
	v_mfma_f32_16x16x32_bf16 v[52:55], v[160:163], v[168:171], v[52:55]
	v_mfma_f32_16x16x32_bf16 v[40:43], v[152:155], v[176:179], v[40:43]
	v_mfma_f32_16x16x32_bf16 v[36:39], v[160:163], v[176:179], v[36:39]
	v_mfma_f32_16x16x32_bf16 v[24:27], v[152:155], v[184:187], v[24:27]
	v_mfma_f32_16x16x32_bf16 v[20:23], v[160:163], v[184:187], v[20:23]
	v_mfma_f32_16x16x32_bf16 v[8:11], v[152:155], v[216:219], v[6:9]
	v_mfma_f32_16x16x32_bf16 v[4:7], v[160:163], v[216:219], v[2:5]
	s_setprio 0
	s_barrier
	s_add_i32 s50, s50, 2
	s_add_u32 s26, s26, 0x100
	s_addc_u32 s27, s27, 0
	s_cmp_gt_u32 s50, 13
	s_cbranch_scc1 .LBB0_3844
